# rstd-table fill at GEMM phase start: issue all units' row-sumsq loads before waiting (was one serialized load round per unit)
# baseline (speedup 1.0000x reference)
.LBB0_74:
	s_or_b64 exec, exec, s[0:1]
	s_waitcnt lgkmcnt(0)
	s_barrier
.LBB0_75:
	v_readlane_b32 s4, v251, 0
	s_mov_b32 s60, s4
	v_readlane_b32 s4, v253, 48
	s_mov_b64 s[0:1], 0
	s_cmp_lt_i32 s4, 21
	s_cbranch_scc1 .LBB0_80
	s_cmp_eq_u32 s4, 21
	s_mov_b64 s[4:5], -1
	s_cbranch_scc0 .LBB0_78
	s_mov_b64 s[4:5], 0

.LBB0_111:
	s_andn2_b64 vcc, exec, s[6:7]
	s_cbranch_vccnz .LBB0_113
	s_mov_b32 s69, 1
	s_add_i32 s59, s10, 1
	s_mov_b32 s68, 0
	s_mov_b32 s8, 0
.LBB0_113:
	s_add_u32 s62, s26, s0
	s_addc_u32 s63, s27, s1
	s_add_u32 s57, s62, 0x2b000000
	v_writelane_b32 v253, s8, 49
	s_addc_u32 s0, s63, 0
	v_writelane_b32 v253, s0, 51
	s_mul_i32 s0, s36, 3
	s_ashr_i32 s61, s60, 31
	v_writelane_b32 v253, s0, 52
	s_lshr_b32 s0, s61, 29
	s_add_i32 s70, s60, s0
	s_and_b32 s0, s70, -8
	s_sub_i32 s58, s60, s0
	s_cmp_lt_i32 s58, 0
	s_cselect_b64 s[0:1], -1, 0
	s_lshl_b32 s86, s36, 10
	s_add_i32 s46, s36, 1
	s_add_i32 s56, s36, -2
	s_add_u32 s76, s62, 0xc000000
	v_writelane_b32 v253, s0, 54
	s_addc_u32 s77, s63, 0
	s_mov_b32 s87, s73
	v_writelane_b32 v253, s1, 55
	s_mov_b64 s[0:1], -1
	s_mov_b64 s[52:53], 0
	s_cmp_lt_i32 s59, 5
	s_mov_b64 s[96:97], 0
	s_mov_b64 s[6:7], 0
	s_cbranch_scc1 .LBB0_545
	v_writelane_b32 v253, s68, 56
	v_writelane_b32 v253, s69, 58
	v_writelane_b32 v253, s86, 60
	s_lshl_b32 s78, s36, 24
	s_cmp_gt_i32 s59, 6
	v_writelane_b32 v253, s87, 61
	v_writelane_b32 v253, s70, 62
	s_cbranch_scc0 .LBB0_123
	s_mov_b32 s37, s73
	s_cmp_gt_i32 s59, 11
	s_cbranch_scc0 .LBB0_124
	s_cmp_gt_i32 s59, 12
	s_mov_b64 s[82:83], 0
	s_cbranch_scc0 .LBB0_127
	s_cmp_eq_u32 s59, 13
	s_mov_b64 s[6:7], -1
	s_cbranch_scc0 .LBB0_126
	s_mov_b64 s[0:1], 0
	v_mov_b32_e32 v2, v202
	v_readlane_b32 s66, v251, 0
	v_ashrrev_i32_e32 v8, 6, v2
	s_movk_i32 s4, 0x4000
	v_lshl_add_u32 v170, s66, 3, v8
	v_cmp_gt_i32_e32 vcc, s4, v170
	s_and_saveexec_b64 s[4:5], vcc
	s_cbranch_execz .LBB0_125
	s_add_u32 s64, s26, s0
	s_addc_u32 s65, s27, s1
	s_add_u32 s6, s64, 0x1b000000
	s_addc_u32 s7, s65, 0
	s_add_u32 s8, s64, 0x1f000000
	s_addc_u32 s9, s65, 0
	s_lshl_b32 s0, s78, 1
	s_add_u32 s0, s6, s0
	s_addc_u32 s1, s7, 0
	s_add_u32 s10, s0, 0xa000000
	s_addc_u32 s11, s1, 0
	s_add_u32 s30, s64, 0x29000000
	s_addc_u32 s31, s65, 0
	s_add_u32 s34, s64, 0x21000000
	s_mov_b32 s38, s46
	v_readlane_b32 s40, v253, 26
	s_addc_u32 s35, s65, 0
	s_lshl_b64 s[0:1], s[86:87], 2
	v_readlane_b32 s46, v253, 32
	v_readlane_b32 s50, v253, 36
	v_readlane_b32 s51, v253, 37
	s_mov_b32 s46, s38
	s_add_u32 s38, s50, s0
	v_readlane_b32 s52, v253, 38
	s_addc_u32 s39, s51, s1
	v_readlane_b32 s41, v253, 27
	v_readlane_b32 s53, v253, 39
	s_add_u32 s40, s52, s0
	v_readlane_b32 s42, v253, 28
	v_readlane_b32 s48, v253, 34
	s_addc_u32 s41, s53, s1
	v_readlane_b32 s43, v253, 29
	v_readlane_b32 s49, v253, 35
	s_add_u32 s42, s48, s0
	s_addc_u32 s43, s49, s1
	s_add_u32 s0, s64, 0x1d000000
	v_readlane_b32 s44, v253, 30
	s_addc_u32 s1, s65, 0
	v_readlane_b32 s45, v253, 31
	s_add_u32 s44, s64, 0x10000000
	s_addc_u32 s45, s65, 0
	v_ashrrev_i32_e32 v10, 2, v170
	s_add_u32 s64, s64, 0xe000000
	s_waitcnt lgkmcnt(0)
	v_and_b32_e32 v9, 63, v2
	s_waitcnt vmcnt(0)
	v_bfe_u32 v0, v2, 6, 2
	v_ashrrev_i32_e32 v11, 31, v10
	s_addc_u32 s65, s65, 0
	v_lshlrev_b64 v[12:13], 13, v[10:11]
	v_lshlrev_b32_e32 v11, 11, v0
	v_lshlrev_b32_e32 v16, 4, v9
	v_lshlrev_b32_e32 v28, 4, v0
	v_lshl_add_u64 v[14:15], s[64:65], 0, v[12:13]
	v_or_b32_e32 v0, v11, v16
	v_and_b32_e32 v3, 15, v2
	v_and_b32_e32 v17, 0xffffffc0, v170
	v_lshl_add_u64 v[14:15], v[14:15], 0, v[0:1]
	global_load_dwordx4 v[60:63], v[14:15], off
	global_load_dwordx4 v[64:67], v[14:15], off offset:1024
	v_or3_b32 v14, v3, v17, v28
	v_ashrrev_i32_e32 v15, 31, v14
	v_lshlrev_b32_e32 v10, 6, v10
	v_lshrrev_b32_e32 v2, 2, v2
	v_lshlrev_b64 v[14:15], 10, v[14:15]
	v_and_b32_e32 v10, 0x3c0, v10
	v_and_b32_e32 v2, 12, v2
	v_or3_b32 v14, v14, v10, v2
	v_lshl_add_u64 v[18:19], s[44:45], 0, v[12:13]
	v_lshl_add_u64 v[12:13], s[0:1], 0, v[12:13]
	v_mov_b32_e32 v17, v1
	v_lshlrev_b64 v[14:15], 1, v[14:15]
	v_lshl_add_u64 v[12:13], v[12:13], 0, v[16:17]
	v_lshl_add_u64 v[20:21], s[6:7], 0, v[14:15]
	global_load_dwordx4 v[48:51], v[12:13], off
	global_load_dwordx4 v[52:55], v[12:13], off offset:1024
	v_lshl_add_u64 v[22:23], s[8:9], 0, v[14:15]
	v_lshl_add_u64 v[24:25], s[10:11], 0, v[14:15]
	v_lshl_add_u64 v[26:27], s[30:31], 0, v[14:15]
	global_load_dwordx2 v[180:181], v[20:21], off
	global_load_dwordx2 v[182:183], v[22:23], off
	global_load_dwordx2 v[150:151], v[24:25], off
	global_load_dwordx2 v[164:165], v[26:27], off
	global_load_dwordx4 v[68:71], v[12:13], off offset:2048
	global_load_dwordx4 v[72:75], v[12:13], off offset:3072
	v_or_b32_e32 v20, 32, v14
	v_mov_b32_e32 v21, v15
	s_movk_i32 s67, 0x1000
	v_lshl_add_u64 v[22:23], s[6:7], 0, v[20:21]
	v_lshl_add_u64 v[24:25], s[8:9], 0, v[20:21]
	v_lshl_add_u64 v[26:27], s[10:11], 0, v[20:21]
	v_lshl_add_u64 v[20:21], s[30:31], 0, v[20:21]
	v_add_co_u32_e32 v12, vcc, s67, v12
	v_lshl_or_b32 v10, v9, 3, v11
	v_mov_b32_e32 v11, v1
	global_load_dwordx2 v[176:177], v[22:23], off
	global_load_dwordx2 v[178:179], v[24:25], off
	global_load_dwordx2 v[146:147], v[26:27], off
	global_load_dwordx2 v[148:149], v[20:21], off
	v_addc_co_u32_e32 v13, vcc, 0, v13, vcc
	v_or_b32_e32 v20, 64, v14
	v_mov_b32_e32 v21, v15
	v_or_b32_e32 v14, 0x60, v14
	v_lshl_add_u64 v[18:19], v[18:19], 0, v[10:11]
	global_load_dwordx4 v[76:79], v[12:13], off
	global_load_dwordx4 v[80:83], v[12:13], off offset:1024
	v_lshl_add_u64 v[22:23], s[6:7], 0, v[20:21]
	global_load_dwordx4 v[84:87], v[12:13], off offset:2048
	global_load_dwordx4 v[88:91], v[12:13], off offset:3072
	global_load_dwordx2 v[186:187], v[18:19], off
	global_load_dwordx2 v[184:185], v[18:19], off offset:512
	global_load_dwordx2 v[58:59], v[18:19], off offset:1024
	global_load_dwordx2 v[56:57], v[18:19], off offset:1536
	global_load_dwordx2 v[172:173], v[22:23], off
	v_lshl_add_u64 v[12:13], s[6:7], 0, v[14:15]
	global_load_dwordx2 v[166:167], v[12:13], off
	v_lshl_add_u64 v[12:13], s[8:9], 0, v[20:21]
	global_load_dwordx2 v[174:175], v[12:13], off
	v_lshl_add_u64 v[12:13], s[8:9], 0, v[14:15]
	global_load_dwordx2 v[168:169], v[12:13], off
	v_lshl_add_u64 v[12:13], s[10:11], 0, v[20:21]
	global_load_dwordx2 v[142:143], v[12:13], off
	v_lshl_add_u64 v[12:13], s[10:11], 0, v[14:15]
	global_load_dwordx2 v[126:127], v[12:13], off
	v_lshl_add_u64 v[12:13], s[30:31], 0, v[20:21]
	global_load_dwordx2 v[144:145], v[12:13], off
	v_lshl_add_u64 v[12:13], s[30:31], 0, v[14:15]
	global_load_dwordx2 v[130:131], v[12:13], off
	v_cmp_lt_i32_e32 vcc, v209, v210
	v_lshl_add_u64 v[92:93], s[64:65], 0, v[0:1]
	v_lshl_add_u64 v[94:95], s[44:45], 0, v[10:11]
	v_cndmask_b32_e32 v9, v208, v209, vcc
	v_cmp_lt_i32_e32 vcc, v211, v210
	v_lshlrev_b32_e32 v188, 2, v9
	v_lshl_add_u64 v[96:97], s[0:1], 0, v[16:17]
	v_cndmask_b32_e32 v9, v208, v211, vcc
	v_lshlrev_b32_e32 v189, 2, v9
	v_or_b32_e32 v190, v28, v3
	v_lshlrev_b32_e32 v0, 4, v8
	v_lshl_add_u32 v191, s66, 7, v0
	s_mov_b64 s[44:45], 0
	v_readlane_b32 s47, v253, 33
	v_readlane_b32 s54, v253, 40
	v_readlane_b32 s55, v253, 41
	s_waitcnt vmcnt(29)
	v_mov_b64_e32 v[8:9], v[60:61]
	s_waitcnt vmcnt(28)
	v_mov_b64_e32 v[12:13], v[64:65]
	v_mov_b64_e32 v[10:11], v[62:63]
	v_mov_b64_e32 v[14:15], v[66:67]
	s_waitcnt vmcnt(27)
	v_mov_b64_e32 v[16:17], v[48:49]
	s_waitcnt vmcnt(26)
	v_mov_b64_e32 v[20:21], v[52:53]
	v_mov_b64_e32 v[18:19], v[50:51]
	v_mov_b64_e32 v[22:23], v[54:55]
	s_waitcnt vmcnt(21)
	v_mov_b64_e32 v[24:25], v[68:69]
	s_waitcnt vmcnt(20)
	v_mov_b64_e32 v[28:29], v[72:73]
	v_mov_b64_e32 v[26:27], v[70:71]
	v_mov_b64_e32 v[30:31], v[74:75]
	v_mov_b64_e32 v[98:99], v[180:181]
	v_mov_b64_e32 v[100:101], v[182:183]
	v_mov_b64_e32 v[102:103], v[150:151]
	v_mov_b64_e32 v[104:105], v[164:165]
	s_waitcnt vmcnt(19)
	v_mov_b64_e32 v[106:107], v[176:177]
	s_waitcnt vmcnt(18)
	v_mov_b64_e32 v[108:109], v[178:179]
	s_waitcnt vmcnt(17)
	v_mov_b64_e32 v[110:111], v[146:147]
	s_waitcnt vmcnt(16)
	v_mov_b64_e32 v[112:113], v[148:149]
	s_waitcnt vmcnt(13)
	v_mov_b64_e32 v[40:41], v[84:85]
	s_waitcnt vmcnt(12)
	v_mov_b64_e32 v[44:45], v[88:89]
	v_mov_b64_e32 v[42:43], v[86:87]
	v_mov_b64_e32 v[32:33], v[76:77]
	v_mov_b64_e32 v[36:37], v[80:81]
	v_mov_b64_e32 v[34:35], v[78:79]
	v_mov_b64_e32 v[38:39], v[82:83]
	v_mov_b64_e32 v[46:47], v[90:91]
	s_waitcnt vmcnt(11)
	v_mov_b64_e32 v[114:115], v[186:187]
	s_waitcnt vmcnt(10)
	v_mov_b64_e32 v[116:117], v[184:185]
	s_waitcnt vmcnt(9)
	v_mov_b64_e32 v[120:121], v[58:59]
	s_waitcnt vmcnt(8)
	v_mov_b64_e32 v[122:123], v[56:57]
	s_waitcnt vmcnt(7)
	v_mov_b64_e32 v[118:119], v[172:173]
	s_waitcnt vmcnt(6)
	v_mov_b64_e32 v[134:135], v[166:167]
	s_waitcnt vmcnt(5)
	v_mov_b64_e32 v[124:125], v[174:175]
	s_waitcnt vmcnt(4)
	v_mov_b64_e32 v[136:137], v[168:169]
	s_waitcnt vmcnt(3)
	v_mov_b64_e32 v[128:129], v[142:143]
	s_waitcnt vmcnt(2)
	v_mov_b64_e32 v[138:139], v[126:127]
	s_waitcnt vmcnt(1)
	v_mov_b64_e32 v[132:133], v[144:145]
	s_waitcnt vmcnt(0)
	v_mov_b64_e32 v[140:141], v[130:131]
	s_branch .LBB0_121

.LBB0_672:
	s_mov_b32 s100, 0
	s_waitcnt vmcnt(0)
	v_cndmask_b32_e64 v0, 0, 1, s[0:1]
	v_cmp_ne_u32_e64 s[4:5], 1, v0
	s_andn2_b64 vcc, exec, s[0:1]
	s_cbranch_vccnz .LBB0_710
	v_readlane_b32 s0, v253, 49
	v_readlane_b32 s1, v253, 52
	s_add_i32 s72, s1, s0
	s_lshl_b64 s[0:1], s[72:73], 20
	s_add_u32 s6, s57, s0
	v_readlane_b32 s0, v253, 51
	s_addc_u32 s7, s0, s1
	s_mov_b64 s[0:1], exec
	v_readlane_b32 s8, v252, 41
	v_readlane_b32 s9, v252, 42
	s_and_b64 s[8:9], s[0:1], s[8:9]
	s_mov_b64 exec, s[8:9]
	s_cbranch_execz .LBB0_675
	v_lshl_or_b32 v2, s44, 8, v202
	s_waitcnt lgkmcnt(0)
	v_ashrrev_i32_e32 v3, 31, v2
	v_lshlrev_b64 v[2:3], 6, v[2:3]
	v_lshl_add_u64 v[2:3], s[6:7], 0, v[2:3]
	s_waitcnt lgkmcnt(0)
	global_load_dwordx4 v[8:11], v[2:3], off
	global_load_dwordx4 v[12:15], v[2:3], off offset:32
	global_load_dwordx4 v[16:19], v[2:3], off offset:16
	global_load_dwordx4 v[20:23], v[2:3], off offset:48
	s_mov_b32 s100, 1

.LBB0_677:
	s_andn2_b64 vcc, exec, s[0:1]
	s_cbranch_vccnz .LBB0_710
	s_mov_b64 s[0:1], exec
	v_readlane_b32 s10, v252, 41
	v_readlane_b32 s11, v252, 42
	s_and_b64 s[10:11], s[0:1], s[10:11]
	s_mov_b64 exec, s[10:11]
	s_cbranch_execz .LBB0_680
	v_lshl_or_b32 v2, s44, 8, v202
	s_waitcnt lgkmcnt(0)
	v_ashrrev_i32_e32 v3, 31, v2
	v_lshlrev_b64 v[2:3], 6, v[2:3]
	v_lshl_add_u64 v[2:3], s[6:7], 0, v[2:3]
	s_waitcnt lgkmcnt(0)
	global_load_dwordx4 v[24:27], v[2:3], off
	global_load_dwordx4 v[28:31], v[2:3], off offset:32
	global_load_dwordx4 v[32:35], v[2:3], off offset:16
	global_load_dwordx4 v[36:39], v[2:3], off offset:48
	s_mov_b32 s100, 2

.LBB0_682:
	s_andn2_b64 vcc, exec, s[0:1]
	s_cbranch_vccnz .LBB0_710
	s_mov_b64 s[0:1], exec
	v_readlane_b32 s10, v252, 41
	v_readlane_b32 s11, v252, 42
	s_and_b64 s[10:11], s[0:1], s[10:11]
	s_mov_b64 exec, s[10:11]
	s_cbranch_execz .LBB0_685
	v_lshl_or_b32 v2, s44, 8, v202
	s_waitcnt lgkmcnt(0)
	v_ashrrev_i32_e32 v3, 31, v2
	v_lshlrev_b64 v[2:3], 6, v[2:3]
	v_lshl_add_u64 v[2:3], s[6:7], 0, v[2:3]
	s_waitcnt lgkmcnt(0)
	global_load_dwordx4 v[40:43], v[2:3], off
	global_load_dwordx4 v[44:47], v[2:3], off offset:32
	global_load_dwordx4 v[48:51], v[2:3], off offset:16
	global_load_dwordx4 v[52:55], v[2:3], off offset:48
	s_mov_b32 s100, 3

.LBB0_687:
	s_andn2_b64 vcc, exec, s[0:1]
	s_cbranch_vccnz .LBB0_710
	s_mov_b64 s[0:1], exec
	v_readlane_b32 s10, v252, 41
	v_readlane_b32 s11, v252, 42
	s_and_b64 s[10:11], s[0:1], s[10:11]
	s_mov_b64 exec, s[10:11]
	s_cbranch_execz .LBB0_690
	v_lshl_or_b32 v2, s44, 8, v202
	s_waitcnt lgkmcnt(0)
	v_ashrrev_i32_e32 v3, 31, v2
	v_lshlrev_b64 v[2:3], 6, v[2:3]
	v_lshl_add_u64 v[2:3], s[6:7], 0, v[2:3]
	s_waitcnt lgkmcnt(0)
	global_load_dwordx4 v[56:59], v[2:3], off
	global_load_dwordx4 v[60:63], v[2:3], off offset:32
	global_load_dwordx4 v[64:67], v[2:3], off offset:16
	global_load_dwordx4 v[68:71], v[2:3], off offset:48
	s_mov_b32 s100, 4

.LBB0_692:
	s_andn2_b64 vcc, exec, s[0:1]
	s_cbranch_vccnz .LBB0_710
	s_mov_b64 s[0:1], exec
	v_readlane_b32 s10, v252, 41
	v_readlane_b32 s11, v252, 42
	s_and_b64 s[10:11], s[0:1], s[10:11]
	s_mov_b64 exec, s[10:11]
	s_cbranch_execz .LBB0_695
	v_lshl_or_b32 v2, s44, 8, v202
	s_waitcnt lgkmcnt(0)
	v_ashrrev_i32_e32 v3, 31, v2
	v_lshlrev_b64 v[2:3], 6, v[2:3]
	v_lshl_add_u64 v[2:3], s[6:7], 0, v[2:3]
	s_waitcnt lgkmcnt(0)
	global_load_dwordx4 v[72:75], v[2:3], off
	global_load_dwordx4 v[76:79], v[2:3], off offset:32
	global_load_dwordx4 v[80:83], v[2:3], off offset:16
	global_load_dwordx4 v[84:87], v[2:3], off offset:48
	s_mov_b32 s100, 5

.LBB0_697:
	s_andn2_b64 vcc, exec, s[0:1]
	s_cbranch_vccnz .LBB0_710
	s_mov_b64 s[0:1], exec
	v_readlane_b32 s10, v252, 41
	v_readlane_b32 s11, v252, 42
	s_and_b64 s[10:11], s[0:1], s[10:11]
	s_mov_b64 exec, s[10:11]
	s_cbranch_execz .LBB0_700
	v_lshl_or_b32 v2, s44, 8, v202
	s_waitcnt lgkmcnt(0)
	v_ashrrev_i32_e32 v3, 31, v2
	v_lshlrev_b64 v[2:3], 6, v[2:3]
	v_lshl_add_u64 v[2:3], s[6:7], 0, v[2:3]
	s_waitcnt lgkmcnt(0)
	global_load_dwordx4 v[88:91], v[2:3], off
	global_load_dwordx4 v[92:95], v[2:3], off offset:32
	global_load_dwordx4 v[96:99], v[2:3], off offset:16
	global_load_dwordx4 v[100:103], v[2:3], off offset:48
	s_mov_b32 s100, 6

.LBB0_702:
	s_andn2_b64 vcc, exec, s[0:1]
	s_cbranch_vccnz .LBB0_710
	s_mov_b64 s[0:1], exec
	v_readlane_b32 s10, v252, 41
	v_readlane_b32 s11, v252, 42
	s_and_b64 s[10:11], s[0:1], s[10:11]
	s_mov_b64 exec, s[10:11]
	s_cbranch_execz .LBB0_705
	v_lshl_or_b32 v2, s44, 8, v202
	s_waitcnt lgkmcnt(0)
	v_ashrrev_i32_e32 v3, 31, v2
	v_lshlrev_b64 v[2:3], 6, v[2:3]
	v_lshl_add_u64 v[2:3], s[6:7], 0, v[2:3]
	s_waitcnt lgkmcnt(0)
	global_load_dwordx4 v[104:107], v[2:3], off
	global_load_dwordx4 v[108:111], v[2:3], off offset:32
	global_load_dwordx4 v[112:115], v[2:3], off offset:16
	global_load_dwordx4 v[116:119], v[2:3], off offset:48
	s_mov_b32 s100, 7

.LBB0_707:
	s_xor_b64 s[8:9], s[8:9], -1
	s_and_saveexec_b64 s[0:1], s[8:9]
	s_cbranch_execz .LBB0_709
	v_lshl_or_b32 v2, s44, 8, v202
	s_waitcnt lgkmcnt(0)
	v_ashrrev_i32_e32 v3, 31, v2
	v_lshlrev_b64 v[2:3], 6, v[2:3]
	v_lshl_add_u64 v[2:3], s[6:7], 0, v[2:3]
	s_waitcnt lgkmcnt(0)
	global_load_dwordx4 v[120:123], v[2:3], off
	global_load_dwordx4 v[124:127], v[2:3], off offset:32
	global_load_dwordx4 v[128:131], v[2:3], off offset:16
	global_load_dwordx4 v[132:135], v[2:3], off offset:48
	s_mov_b32 s100, 8

.LBB0_710:
	s_cmp_eq_u32 s100, 0
	s_cbranch_scc1 .Lrt_done_A
	s_waitcnt vmcnt(0)
	s_mov_b32 s101, 0x800000
	v_mov_b32_e32 v2, v8
	v_mov_b32_e32 v3, v12
	v_mov_b32_e32 v12, v9
	v_mov_b32_e32 v8, v10
	v_mov_b32_e32 v9, v14
	v_mov_b32_e32 v14, v11
	v_mov_b32_e32 v10, v16
	v_mov_b32_e32 v11, v20
	v_mov_b32_e32 v20, v17
	v_mov_b32_e32 v16, v18
	v_mov_b32_e32 v17, v22
	v_mov_b32_e32 v22, v19
	v_pk_add_f32 v[2:3], v[2:3], v[12:13]
	v_pk_add_f32 v[8:9], v[8:9], v[14:15]
	v_pk_add_f32 v[10:11], v[10:11], v[20:21]
	v_pk_add_f32 v[12:13], v[16:17], v[22:23]
	v_pk_add_f32 v[2:3], v[2:3], v[8:9]
	v_pk_add_f32 v[8:9], v[10:11], v[12:13]
	s_nop 0
	v_pk_add_f32 v[2:3], v[2:3], v[8:9]
	s_nop 0
	v_add_f32_e32 v0, v2, v3
	v_fmamk_f32 v0, v0, 0x3a800000, v206
	v_mul_f32_e32 v2, 0x4b800000, v0
	v_cmp_gt_f32_e32 vcc, s101, v0
	s_nop 1
	v_cndmask_b32_e32 v0, v0, v2, vcc
	v_rsq_f32_e32 v0, v0
	s_nop 0
	v_mul_f32_e32 v2, 0x45800000, v0
	v_cndmask_b32_e32 v0, v0, v2, vcc
	ds_write_b32 v203, v0
	s_cmp_lt_u32 s100, 2
	s_cbranch_scc1 .Lrt_done_A
	v_mov_b32_e32 v2, v24
	v_mov_b32_e32 v3, v28
	v_mov_b32_e32 v28, v25
	v_mov_b32_e32 v24, v26
	v_mov_b32_e32 v25, v30
	v_mov_b32_e32 v30, v27
	v_mov_b32_e32 v26, v32
	v_mov_b32_e32 v27, v36
	v_mov_b32_e32 v36, v33
	v_mov_b32_e32 v32, v34
	v_mov_b32_e32 v33, v38
	v_mov_b32_e32 v38, v35
	v_pk_add_f32 v[2:3], v[2:3], v[28:29]
	v_pk_add_f32 v[24:25], v[24:25], v[30:31]
	v_pk_add_f32 v[26:27], v[26:27], v[36:37]
	v_pk_add_f32 v[28:29], v[32:33], v[38:39]
	v_pk_add_f32 v[2:3], v[2:3], v[24:25]
	v_pk_add_f32 v[24:25], v[26:27], v[28:29]
	s_nop 0
	v_pk_add_f32 v[2:3], v[2:3], v[24:25]
	s_nop 0
	v_add_f32_e32 v0, v2, v3
	v_fmamk_f32 v0, v0, 0x3a800000, v206
	v_mul_f32_e32 v2, 0x4b800000, v0
	v_cmp_gt_f32_e32 vcc, s101, v0
	s_nop 1
	v_cndmask_b32_e32 v0, v0, v2, vcc
	v_rsq_f32_e32 v0, v0
	s_nop 0
	v_mul_f32_e32 v2, 0x45800000, v0
	v_cndmask_b32_e32 v0, v0, v2, vcc
	ds_write_b32 v203, v0 offset:1024
	s_cmp_lt_u32 s100, 3
	s_cbranch_scc1 .Lrt_done_A
	v_mov_b32_e32 v2, v40
	v_mov_b32_e32 v3, v44
	v_mov_b32_e32 v44, v41
	v_mov_b32_e32 v40, v42
	v_mov_b32_e32 v41, v46
	v_mov_b32_e32 v46, v43
	v_mov_b32_e32 v42, v48
	v_mov_b32_e32 v43, v52
	v_mov_b32_e32 v52, v49
	v_mov_b32_e32 v48, v50
	v_mov_b32_e32 v49, v54
	v_mov_b32_e32 v54, v51
	v_pk_add_f32 v[2:3], v[2:3], v[44:45]
	v_pk_add_f32 v[40:41], v[40:41], v[46:47]
	v_pk_add_f32 v[42:43], v[42:43], v[52:53]
	v_pk_add_f32 v[44:45], v[48:49], v[54:55]
	v_pk_add_f32 v[2:3], v[2:3], v[40:41]
	v_pk_add_f32 v[40:41], v[42:43], v[44:45]
	s_nop 0
	v_pk_add_f32 v[2:3], v[2:3], v[40:41]
	s_nop 0
	v_add_f32_e32 v0, v2, v3
	v_fmamk_f32 v0, v0, 0x3a800000, v206
	v_mul_f32_e32 v2, 0x4b800000, v0
	v_cmp_gt_f32_e32 vcc, s101, v0
	s_nop 1
	v_cndmask_b32_e32 v0, v0, v2, vcc
	v_rsq_f32_e32 v0, v0
	s_nop 0
	v_mul_f32_e32 v2, 0x45800000, v0
	v_cndmask_b32_e32 v0, v0, v2, vcc
	ds_write_b32 v203, v0 offset:2048
	s_cmp_lt_u32 s100, 4
	s_cbranch_scc1 .Lrt_done_A
	v_mov_b32_e32 v2, v56
	v_mov_b32_e32 v3, v60
	v_mov_b32_e32 v60, v57
	v_mov_b32_e32 v56, v58
	v_mov_b32_e32 v57, v62
	v_mov_b32_e32 v62, v59
	v_mov_b32_e32 v58, v64
	v_mov_b32_e32 v59, v68
	v_mov_b32_e32 v68, v65
	v_mov_b32_e32 v64, v66
	v_mov_b32_e32 v65, v70
	v_mov_b32_e32 v70, v67
	v_pk_add_f32 v[2:3], v[2:3], v[60:61]
	v_pk_add_f32 v[56:57], v[56:57], v[62:63]
	v_pk_add_f32 v[58:59], v[58:59], v[68:69]
	v_pk_add_f32 v[60:61], v[64:65], v[70:71]
	v_pk_add_f32 v[2:3], v[2:3], v[56:57]
	v_pk_add_f32 v[56:57], v[58:59], v[60:61]
	s_nop 0
	v_pk_add_f32 v[2:3], v[2:3], v[56:57]
	s_nop 0
	v_add_f32_e32 v0, v2, v3
	v_fmamk_f32 v0, v0, 0x3a800000, v206
	v_mul_f32_e32 v2, 0x4b800000, v0
	v_cmp_gt_f32_e32 vcc, s101, v0
	s_nop 1
	v_cndmask_b32_e32 v0, v0, v2, vcc
	v_rsq_f32_e32 v0, v0
	s_nop 0
	v_mul_f32_e32 v2, 0x45800000, v0
	v_cndmask_b32_e32 v0, v0, v2, vcc
	ds_write_b32 v203, v0 offset:3072
	s_cmp_lt_u32 s100, 5
	s_cbranch_scc1 .Lrt_done_A
	v_mov_b32_e32 v2, v72
	v_mov_b32_e32 v3, v76
	v_mov_b32_e32 v76, v73
	v_mov_b32_e32 v72, v74
	v_mov_b32_e32 v73, v78
	v_mov_b32_e32 v78, v75
	v_mov_b32_e32 v74, v80
	v_mov_b32_e32 v75, v84
	v_mov_b32_e32 v84, v81
	v_mov_b32_e32 v80, v82
	v_mov_b32_e32 v81, v86
	v_mov_b32_e32 v86, v83
	v_pk_add_f32 v[2:3], v[2:3], v[76:77]
	v_pk_add_f32 v[72:73], v[72:73], v[78:79]
	v_pk_add_f32 v[74:75], v[74:75], v[84:85]
	v_pk_add_f32 v[76:77], v[80:81], v[86:87]
	v_pk_add_f32 v[2:3], v[2:3], v[72:73]
	v_pk_add_f32 v[72:73], v[74:75], v[76:77]
	s_nop 0
	v_pk_add_f32 v[2:3], v[2:3], v[72:73]
	s_nop 0
	v_add_f32_e32 v0, v2, v3
	v_fmamk_f32 v0, v0, 0x3a800000, v206
	v_mul_f32_e32 v2, 0x4b800000, v0
	v_cmp_gt_f32_e32 vcc, s101, v0
	s_nop 1
	v_cndmask_b32_e32 v0, v0, v2, vcc
	v_rsq_f32_e32 v0, v0
	s_nop 0
	v_mul_f32_e32 v2, 0x45800000, v0
	v_cndmask_b32_e32 v0, v0, v2, vcc
	ds_write_b32 v203, v0 offset:4096
	s_cmp_lt_u32 s100, 6
	s_cbranch_scc1 .Lrt_done_A
	v_mov_b32_e32 v2, v88
	v_mov_b32_e32 v3, v92
	v_mov_b32_e32 v92, v89
	v_mov_b32_e32 v88, v90
	v_mov_b32_e32 v89, v94
	v_mov_b32_e32 v94, v91
	v_mov_b32_e32 v90, v96
	v_mov_b32_e32 v91, v100
	v_mov_b32_e32 v100, v97
	v_mov_b32_e32 v96, v98
	v_mov_b32_e32 v97, v102
	v_mov_b32_e32 v102, v99
	v_pk_add_f32 v[2:3], v[2:3], v[92:93]
	v_pk_add_f32 v[88:89], v[88:89], v[94:95]
	v_pk_add_f32 v[90:91], v[90:91], v[100:101]
	v_pk_add_f32 v[92:93], v[96:97], v[102:103]
	v_pk_add_f32 v[2:3], v[2:3], v[88:89]
	v_pk_add_f32 v[88:89], v[90:91], v[92:93]
	s_nop 0
	v_pk_add_f32 v[2:3], v[2:3], v[88:89]
	s_nop 0
	v_add_f32_e32 v0, v2, v3
	v_fmamk_f32 v0, v0, 0x3a800000, v206
	v_mul_f32_e32 v2, 0x4b800000, v0
	v_cmp_gt_f32_e32 vcc, s101, v0
	s_nop 1
	v_cndmask_b32_e32 v0, v0, v2, vcc
	v_rsq_f32_e32 v0, v0
	s_nop 0
	v_mul_f32_e32 v2, 0x45800000, v0
	v_cndmask_b32_e32 v0, v0, v2, vcc
	ds_write_b32 v203, v0 offset:5120
	s_cmp_lt_u32 s100, 7
	s_cbranch_scc1 .Lrt_done_A
	v_mov_b32_e32 v2, v104
	v_mov_b32_e32 v3, v108
	v_mov_b32_e32 v108, v105
	v_mov_b32_e32 v104, v106
	v_mov_b32_e32 v105, v110
	v_mov_b32_e32 v110, v107
	v_mov_b32_e32 v106, v112
	v_mov_b32_e32 v107, v116
	v_mov_b32_e32 v116, v113
	v_mov_b32_e32 v112, v114
	v_mov_b32_e32 v113, v118
	v_mov_b32_e32 v118, v115
	v_pk_add_f32 v[2:3], v[2:3], v[108:109]
	v_pk_add_f32 v[104:105], v[104:105], v[110:111]
	v_pk_add_f32 v[106:107], v[106:107], v[116:117]
	v_pk_add_f32 v[108:109], v[112:113], v[118:119]
	v_pk_add_f32 v[2:3], v[2:3], v[104:105]
	v_pk_add_f32 v[104:105], v[106:107], v[108:109]
	s_nop 0
	v_pk_add_f32 v[2:3], v[2:3], v[104:105]
	s_nop 0
	v_add_f32_e32 v0, v2, v3
	v_fmamk_f32 v0, v0, 0x3a800000, v206
	v_mul_f32_e32 v2, 0x4b800000, v0
	v_cmp_gt_f32_e32 vcc, s101, v0
	s_nop 1
	v_cndmask_b32_e32 v0, v0, v2, vcc
	v_rsq_f32_e32 v0, v0
	s_nop 0
	v_mul_f32_e32 v2, 0x45800000, v0
	v_cndmask_b32_e32 v0, v0, v2, vcc
	ds_write_b32 v203, v0 offset:6144
	s_cmp_lt_u32 s100, 8
	s_cbranch_scc1 .Lrt_done_A
	v_mov_b32_e32 v2, v120
	v_mov_b32_e32 v3, v124
	v_mov_b32_e32 v124, v121
	v_mov_b32_e32 v120, v122
	v_mov_b32_e32 v121, v126
	v_mov_b32_e32 v126, v123
	v_mov_b32_e32 v122, v128
	v_mov_b32_e32 v123, v132
	v_mov_b32_e32 v132, v129
	v_mov_b32_e32 v128, v130
	v_mov_b32_e32 v129, v134
	v_mov_b32_e32 v134, v131
	v_pk_add_f32 v[2:3], v[2:3], v[124:125]
	v_pk_add_f32 v[120:121], v[120:121], v[126:127]
	v_pk_add_f32 v[122:123], v[122:123], v[132:133]
	v_pk_add_f32 v[124:125], v[128:129], v[134:135]
	v_pk_add_f32 v[2:3], v[2:3], v[120:121]
	v_pk_add_f32 v[120:121], v[122:123], v[124:125]
	s_nop 0
	v_pk_add_f32 v[2:3], v[2:3], v[120:121]
	s_nop 0
	v_add_f32_e32 v0, v2, v3
	v_fmamk_f32 v0, v0, 0x3a800000, v206
	v_mul_f32_e32 v2, 0x4b800000, v0
	v_cmp_gt_f32_e32 vcc, s101, v0
	s_nop 1
	v_cndmask_b32_e32 v0, v0, v2, vcc
	v_rsq_f32_e32 v0, v0
	s_nop 0
	v_mul_f32_e32 v2, 0x45800000, v0
	v_cndmask_b32_e32 v0, v0, v2, vcc
	ds_write_b32 v203, v0 offset:7168

.LBB0_762:
	s_mov_b32 s100, 0
	v_cndmask_b32_e64 v2, 0, 1, s[0:1]
	v_cmp_ne_u32_e64 s[4:5], 1, v2
	s_andn2_b64 vcc, exec, s[0:1]
	s_cbranch_vccnz .LBB0_800
	s_add_i32 s0, s46, s54
	s_mov_b32 s1, s73
	s_lshl_b64 s[0:1], s[0:1], 20
	s_add_u32 s8, s57, s0
	v_readlane_b32 s0, v253, 51
	s_addc_u32 s9, s0, s1
	s_add_u32 s10, s62, 0x2b600000
	s_addc_u32 s11, s63, 0
	s_and_b64 s[0:1], s[6:7], exec
	s_cselect_b32 s9, s11, s9
	s_cselect_b32 s8, s10, s8
	s_mov_b64 s[0:1], exec
	v_readlane_b32 s10, v252, 41
	v_readlane_b32 s11, v252, 42
	s_and_b64 s[10:11], s[0:1], s[10:11]
	s_mov_b64 exec, s[10:11]
	s_cbranch_execz .LBB0_765
	v_lshl_or_b32 v2, s65, 8, v202
	s_waitcnt lgkmcnt(0)
	v_ashrrev_i32_e32 v3, 31, v2
	v_lshlrev_b64 v[2:3], 6, v[2:3]
	v_lshl_add_u64 v[2:3], s[8:9], 0, v[2:3]
	s_waitcnt lgkmcnt(0)
	global_load_dwordx4 v[8:11], v[2:3], off
	global_load_dwordx4 v[12:15], v[2:3], off offset:32
	global_load_dwordx4 v[16:19], v[2:3], off offset:16
	global_load_dwordx4 v[20:23], v[2:3], off offset:48
	s_mov_b32 s100, 1

.LBB0_767:
	s_andn2_b64 vcc, exec, s[0:1]
	s_cbranch_vccnz .LBB0_800
	s_mov_b64 s[0:1], exec
	v_readlane_b32 s30, v252, 41
	v_readlane_b32 s31, v252, 42
	s_and_b64 s[30:31], s[0:1], s[30:31]
	s_mov_b64 exec, s[30:31]
	s_cbranch_execz .LBB0_770
	v_lshl_or_b32 v2, s65, 8, v202
	v_ashrrev_i32_e32 v3, 31, v2
	v_lshlrev_b64 v[2:3], 6, v[2:3]
	v_lshl_add_u64 v[2:3], s[8:9], 0, v[2:3]
	s_waitcnt lgkmcnt(0)
	global_load_dwordx4 v[24:27], v[2:3], off
	global_load_dwordx4 v[28:31], v[2:3], off offset:32
	global_load_dwordx4 v[32:35], v[2:3], off offset:16
	global_load_dwordx4 v[36:39], v[2:3], off offset:48
	s_mov_b32 s100, 2

.LBB0_772:
	s_andn2_b64 vcc, exec, s[0:1]
	s_cbranch_vccnz .LBB0_800
	s_mov_b64 s[0:1], exec
	v_readlane_b32 s30, v252, 41
	v_readlane_b32 s31, v252, 42
	s_and_b64 s[30:31], s[0:1], s[30:31]
	s_mov_b64 exec, s[30:31]
	s_cbranch_execz .LBB0_775
	v_lshl_or_b32 v2, s65, 8, v202
	v_ashrrev_i32_e32 v3, 31, v2
	v_lshlrev_b64 v[2:3], 6, v[2:3]
	v_lshl_add_u64 v[2:3], s[8:9], 0, v[2:3]
	s_waitcnt lgkmcnt(0)
	global_load_dwordx4 v[40:43], v[2:3], off
	global_load_dwordx4 v[44:47], v[2:3], off offset:32
	global_load_dwordx4 v[48:51], v[2:3], off offset:16
	global_load_dwordx4 v[52:55], v[2:3], off offset:48
	s_mov_b32 s100, 3

.LBB0_777:
	s_andn2_b64 vcc, exec, s[0:1]
	s_cbranch_vccnz .LBB0_800
	s_mov_b64 s[0:1], exec
	v_readlane_b32 s30, v252, 41
	v_readlane_b32 s31, v252, 42
	s_and_b64 s[30:31], s[0:1], s[30:31]
	s_mov_b64 exec, s[30:31]
	s_cbranch_execz .LBB0_780
	v_lshl_or_b32 v2, s65, 8, v202
	v_ashrrev_i32_e32 v3, 31, v2
	v_lshlrev_b64 v[2:3], 6, v[2:3]
	v_lshl_add_u64 v[2:3], s[8:9], 0, v[2:3]
	s_waitcnt lgkmcnt(0)
	global_load_dwordx4 v[56:59], v[2:3], off
	global_load_dwordx4 v[60:63], v[2:3], off offset:32
	global_load_dwordx4 v[64:67], v[2:3], off offset:16
	global_load_dwordx4 v[68:71], v[2:3], off offset:48
	s_mov_b32 s100, 4

.LBB0_782:
	s_andn2_b64 vcc, exec, s[0:1]
	s_cbranch_vccnz .LBB0_800
	s_mov_b64 s[0:1], exec
	v_readlane_b32 s30, v252, 41
	v_readlane_b32 s31, v252, 42
	s_and_b64 s[30:31], s[0:1], s[30:31]
	s_mov_b64 exec, s[30:31]
	s_cbranch_execz .LBB0_785
	v_lshl_or_b32 v2, s65, 8, v202
	v_ashrrev_i32_e32 v3, 31, v2
	v_lshlrev_b64 v[2:3], 6, v[2:3]
	v_lshl_add_u64 v[2:3], s[8:9], 0, v[2:3]
	s_waitcnt lgkmcnt(0)
	global_load_dwordx4 v[72:75], v[2:3], off
	global_load_dwordx4 v[76:79], v[2:3], off offset:32
	global_load_dwordx4 v[80:83], v[2:3], off offset:16
	global_load_dwordx4 v[84:87], v[2:3], off offset:48
	s_mov_b32 s100, 5

.LBB0_787:
	s_andn2_b64 vcc, exec, s[0:1]
	s_cbranch_vccnz .LBB0_800
	s_mov_b64 s[0:1], exec
	v_readlane_b32 s30, v252, 41
	v_readlane_b32 s31, v252, 42
	s_and_b64 s[30:31], s[0:1], s[30:31]
	s_mov_b64 exec, s[30:31]
	s_cbranch_execz .LBB0_790
	v_lshl_or_b32 v2, s65, 8, v202
	v_ashrrev_i32_e32 v3, 31, v2
	v_lshlrev_b64 v[2:3], 6, v[2:3]
	v_lshl_add_u64 v[2:3], s[8:9], 0, v[2:3]
	s_waitcnt lgkmcnt(0)
	global_load_dwordx4 v[88:91], v[2:3], off
	global_load_dwordx4 v[92:95], v[2:3], off offset:32
	global_load_dwordx4 v[96:99], v[2:3], off offset:16
	global_load_dwordx4 v[100:103], v[2:3], off offset:48
	s_mov_b32 s100, 6

.LBB0_792:
	s_andn2_b64 vcc, exec, s[0:1]
	s_cbranch_vccnz .LBB0_800
	s_mov_b64 s[0:1], exec
	v_readlane_b32 s30, v252, 41
	v_readlane_b32 s31, v252, 42
	s_and_b64 s[30:31], s[0:1], s[30:31]
	s_mov_b64 exec, s[30:31]
	s_cbranch_execz .LBB0_795
	v_lshl_or_b32 v2, s65, 8, v202
	v_ashrrev_i32_e32 v3, 31, v2
	v_lshlrev_b64 v[2:3], 6, v[2:3]
	v_lshl_add_u64 v[2:3], s[8:9], 0, v[2:3]
	s_waitcnt lgkmcnt(0)
	global_load_dwordx4 v[104:107], v[2:3], off
	global_load_dwordx4 v[108:111], v[2:3], off offset:32
	global_load_dwordx4 v[112:115], v[2:3], off offset:16
	global_load_dwordx4 v[116:119], v[2:3], off offset:48
	s_mov_b32 s100, 7

.LBB0_797:
	s_xor_b64 s[10:11], s[10:11], -1
	s_and_saveexec_b64 s[0:1], s[10:11]
	s_cbranch_execz .LBB0_799
	v_lshl_or_b32 v2, s65, 8, v202
	v_ashrrev_i32_e32 v3, 31, v2
	v_lshlrev_b64 v[2:3], 6, v[2:3]
	v_lshl_add_u64 v[2:3], s[8:9], 0, v[2:3]
	s_waitcnt lgkmcnt(0)
	global_load_dwordx4 v[120:123], v[2:3], off
	global_load_dwordx4 v[124:127], v[2:3], off offset:32
	global_load_dwordx4 v[128:131], v[2:3], off offset:16
	global_load_dwordx4 v[132:135], v[2:3], off offset:48
	s_mov_b32 s100, 8

.LBB0_800:
	s_cmp_eq_u32 s100, 0
	s_cbranch_scc1 .Lrt_done_B
	s_waitcnt vmcnt(0)
	s_mov_b32 s101, 0x800000
	v_mov_b32_e32 v2, v8
	v_mov_b32_e32 v3, v12
	v_mov_b32_e32 v12, v9
	v_mov_b32_e32 v8, v10
	v_mov_b32_e32 v9, v14
	v_mov_b32_e32 v14, v11
	v_mov_b32_e32 v10, v16
	v_mov_b32_e32 v11, v20
	v_mov_b32_e32 v20, v17
	v_mov_b32_e32 v16, v18
	v_mov_b32_e32 v17, v22
	v_mov_b32_e32 v22, v19
	v_pk_add_f32 v[2:3], v[2:3], v[12:13]
	v_pk_add_f32 v[8:9], v[8:9], v[14:15]
	v_pk_add_f32 v[10:11], v[10:11], v[20:21]
	v_pk_add_f32 v[12:13], v[16:17], v[22:23]
	v_pk_add_f32 v[2:3], v[2:3], v[8:9]
	v_pk_add_f32 v[8:9], v[10:11], v[12:13]
	s_nop 0
	v_pk_add_f32 v[2:3], v[2:3], v[8:9]
	s_nop 0
	v_add_f32_e32 v2, v2, v3
	v_fmamk_f32 v2, v2, 0x3a800000, v206
	v_mul_f32_e32 v3, 0x4b800000, v2
	v_cmp_gt_f32_e32 vcc, s101, v2
	s_nop 1
	v_cndmask_b32_e32 v2, v2, v3, vcc
	v_rsq_f32_e32 v2, v2
	s_nop 0
	v_mul_f32_e32 v3, 0x45800000, v2
	v_cndmask_b32_e32 v2, v2, v3, vcc
	ds_write_b32 v203, v2
	s_cmp_lt_u32 s100, 2
	s_cbranch_scc1 .Lrt_done_B
	v_mov_b32_e32 v2, v24
	v_mov_b32_e32 v3, v28
	v_mov_b32_e32 v28, v25
	v_mov_b32_e32 v24, v26
	v_mov_b32_e32 v25, v30
	v_mov_b32_e32 v30, v27
	v_mov_b32_e32 v26, v32
	v_mov_b32_e32 v27, v36
	v_mov_b32_e32 v36, v33
	v_mov_b32_e32 v32, v34
	v_mov_b32_e32 v33, v38
	v_mov_b32_e32 v38, v35
	v_pk_add_f32 v[2:3], v[2:3], v[28:29]
	v_pk_add_f32 v[24:25], v[24:25], v[30:31]
	v_pk_add_f32 v[26:27], v[26:27], v[36:37]
	v_pk_add_f32 v[28:29], v[32:33], v[38:39]
	v_pk_add_f32 v[2:3], v[2:3], v[24:25]
	v_pk_add_f32 v[24:25], v[26:27], v[28:29]
	s_nop 0
	v_pk_add_f32 v[2:3], v[2:3], v[24:25]
	s_nop 0
	v_add_f32_e32 v2, v2, v3
	v_fmamk_f32 v2, v2, 0x3a800000, v206
	v_mul_f32_e32 v3, 0x4b800000, v2
	v_cmp_gt_f32_e32 vcc, s101, v2
	s_nop 1
	v_cndmask_b32_e32 v2, v2, v3, vcc
	v_rsq_f32_e32 v2, v2
	s_nop 0
	v_mul_f32_e32 v3, 0x45800000, v2
	v_cndmask_b32_e32 v2, v2, v3, vcc
	ds_write_b32 v203, v2 offset:1024
	s_cmp_lt_u32 s100, 3
	s_cbranch_scc1 .Lrt_done_B
	v_mov_b32_e32 v2, v40
	v_mov_b32_e32 v3, v44
	v_mov_b32_e32 v44, v41
	v_mov_b32_e32 v40, v42
	v_mov_b32_e32 v41, v46
	v_mov_b32_e32 v46, v43
	v_mov_b32_e32 v42, v48
	v_mov_b32_e32 v43, v52
	v_mov_b32_e32 v52, v49
	v_mov_b32_e32 v48, v50
	v_mov_b32_e32 v49, v54
	v_mov_b32_e32 v54, v51
	v_pk_add_f32 v[2:3], v[2:3], v[44:45]
	v_pk_add_f32 v[40:41], v[40:41], v[46:47]
	v_pk_add_f32 v[42:43], v[42:43], v[52:53]
	v_pk_add_f32 v[44:45], v[48:49], v[54:55]
	v_pk_add_f32 v[2:3], v[2:3], v[40:41]
	v_pk_add_f32 v[40:41], v[42:43], v[44:45]
	s_nop 0
	v_pk_add_f32 v[2:3], v[2:3], v[40:41]
	s_nop 0
	v_add_f32_e32 v2, v2, v3
	v_fmamk_f32 v2, v2, 0x3a800000, v206
	v_mul_f32_e32 v3, 0x4b800000, v2
	v_cmp_gt_f32_e32 vcc, s101, v2
	s_nop 1
	v_cndmask_b32_e32 v2, v2, v3, vcc
	v_rsq_f32_e32 v2, v2
	s_nop 0
	v_mul_f32_e32 v3, 0x45800000, v2
	v_cndmask_b32_e32 v2, v2, v3, vcc
	ds_write_b32 v203, v2 offset:2048
	s_cmp_lt_u32 s100, 4
	s_cbranch_scc1 .Lrt_done_B
	v_mov_b32_e32 v2, v56
	v_mov_b32_e32 v3, v60
	v_mov_b32_e32 v60, v57
	v_mov_b32_e32 v56, v58
	v_mov_b32_e32 v57, v62
	v_mov_b32_e32 v62, v59
	v_mov_b32_e32 v58, v64
	v_mov_b32_e32 v59, v68
	v_mov_b32_e32 v68, v65
	v_mov_b32_e32 v64, v66
	v_mov_b32_e32 v65, v70
	v_mov_b32_e32 v70, v67
	v_pk_add_f32 v[2:3], v[2:3], v[60:61]
	v_pk_add_f32 v[56:57], v[56:57], v[62:63]
	v_pk_add_f32 v[58:59], v[58:59], v[68:69]
	v_pk_add_f32 v[60:61], v[64:65], v[70:71]
	v_pk_add_f32 v[2:3], v[2:3], v[56:57]
	v_pk_add_f32 v[56:57], v[58:59], v[60:61]
	s_nop 0
	v_pk_add_f32 v[2:3], v[2:3], v[56:57]
	s_nop 0
	v_add_f32_e32 v2, v2, v3
	v_fmamk_f32 v2, v2, 0x3a800000, v206
	v_mul_f32_e32 v3, 0x4b800000, v2
	v_cmp_gt_f32_e32 vcc, s101, v2
	s_nop 1
	v_cndmask_b32_e32 v2, v2, v3, vcc
	v_rsq_f32_e32 v2, v2
	s_nop 0
	v_mul_f32_e32 v3, 0x45800000, v2
	v_cndmask_b32_e32 v2, v2, v3, vcc
	ds_write_b32 v203, v2 offset:3072
	s_cmp_lt_u32 s100, 5
	s_cbranch_scc1 .Lrt_done_B
	v_mov_b32_e32 v2, v72
	v_mov_b32_e32 v3, v76
	v_mov_b32_e32 v76, v73
	v_mov_b32_e32 v72, v74
	v_mov_b32_e32 v73, v78
	v_mov_b32_e32 v78, v75
	v_mov_b32_e32 v74, v80
	v_mov_b32_e32 v75, v84
	v_mov_b32_e32 v84, v81
	v_mov_b32_e32 v80, v82
	v_mov_b32_e32 v81, v86
	v_mov_b32_e32 v86, v83
	v_pk_add_f32 v[2:3], v[2:3], v[76:77]
	v_pk_add_f32 v[72:73], v[72:73], v[78:79]
	v_pk_add_f32 v[74:75], v[74:75], v[84:85]
	v_pk_add_f32 v[76:77], v[80:81], v[86:87]
	v_pk_add_f32 v[2:3], v[2:3], v[72:73]
	v_pk_add_f32 v[72:73], v[74:75], v[76:77]
	s_nop 0
	v_pk_add_f32 v[2:3], v[2:3], v[72:73]
	s_nop 0
	v_add_f32_e32 v2, v2, v3
	v_fmamk_f32 v2, v2, 0x3a800000, v206
	v_mul_f32_e32 v3, 0x4b800000, v2
	v_cmp_gt_f32_e32 vcc, s101, v2
	s_nop 1
	v_cndmask_b32_e32 v2, v2, v3, vcc
	v_rsq_f32_e32 v2, v2
	s_nop 0
	v_mul_f32_e32 v3, 0x45800000, v2
	v_cndmask_b32_e32 v2, v2, v3, vcc
	ds_write_b32 v203, v2 offset:4096
	s_cmp_lt_u32 s100, 6
	s_cbranch_scc1 .Lrt_done_B
	v_mov_b32_e32 v2, v88
	v_mov_b32_e32 v3, v92
	v_mov_b32_e32 v92, v89
	v_mov_b32_e32 v88, v90
	v_mov_b32_e32 v89, v94
	v_mov_b32_e32 v94, v91
	v_mov_b32_e32 v90, v96
	v_mov_b32_e32 v91, v100
	v_mov_b32_e32 v100, v97
	v_mov_b32_e32 v96, v98
	v_mov_b32_e32 v97, v102
	v_mov_b32_e32 v102, v99
	v_pk_add_f32 v[2:3], v[2:3], v[92:93]
	v_pk_add_f32 v[88:89], v[88:89], v[94:95]
	v_pk_add_f32 v[90:91], v[90:91], v[100:101]
	v_pk_add_f32 v[92:93], v[96:97], v[102:103]
	v_pk_add_f32 v[2:3], v[2:3], v[88:89]
	v_pk_add_f32 v[88:89], v[90:91], v[92:93]
	s_nop 0
	v_pk_add_f32 v[2:3], v[2:3], v[88:89]
	s_nop 0
	v_add_f32_e32 v2, v2, v3
	v_fmamk_f32 v2, v2, 0x3a800000, v206
	v_mul_f32_e32 v3, 0x4b800000, v2
	v_cmp_gt_f32_e32 vcc, s101, v2
	s_nop 1
	v_cndmask_b32_e32 v2, v2, v3, vcc
	v_rsq_f32_e32 v2, v2
	s_nop 0
	v_mul_f32_e32 v3, 0x45800000, v2
	v_cndmask_b32_e32 v2, v2, v3, vcc
	ds_write_b32 v203, v2 offset:5120
	s_cmp_lt_u32 s100, 7
	s_cbranch_scc1 .Lrt_done_B
	v_mov_b32_e32 v2, v104
	v_mov_b32_e32 v3, v108
	v_mov_b32_e32 v108, v105
	v_mov_b32_e32 v104, v106
	v_mov_b32_e32 v105, v110
	v_mov_b32_e32 v110, v107
	v_mov_b32_e32 v106, v112
	v_mov_b32_e32 v107, v116
	v_mov_b32_e32 v116, v113
	v_mov_b32_e32 v112, v114
	v_mov_b32_e32 v113, v118
	v_mov_b32_e32 v118, v115
	v_pk_add_f32 v[2:3], v[2:3], v[108:109]
	v_pk_add_f32 v[104:105], v[104:105], v[110:111]
	v_pk_add_f32 v[106:107], v[106:107], v[116:117]
	v_pk_add_f32 v[108:109], v[112:113], v[118:119]
	v_pk_add_f32 v[2:3], v[2:3], v[104:105]
	v_pk_add_f32 v[104:105], v[106:107], v[108:109]
	s_nop 0
	v_pk_add_f32 v[2:3], v[2:3], v[104:105]
	s_nop 0
	v_add_f32_e32 v2, v2, v3
	v_fmamk_f32 v2, v2, 0x3a800000, v206
	v_mul_f32_e32 v3, 0x4b800000, v2
	v_cmp_gt_f32_e32 vcc, s101, v2
	s_nop 1
	v_cndmask_b32_e32 v2, v2, v3, vcc
	v_rsq_f32_e32 v2, v2
	s_nop 0
	v_mul_f32_e32 v3, 0x45800000, v2
	v_cndmask_b32_e32 v2, v2, v3, vcc
	ds_write_b32 v203, v2 offset:6144
	s_cmp_lt_u32 s100, 8
	s_cbranch_scc1 .Lrt_done_B
	v_mov_b32_e32 v2, v120
	v_mov_b32_e32 v3, v124
	v_mov_b32_e32 v124, v121
	v_mov_b32_e32 v120, v122
	v_mov_b32_e32 v121, v126
	v_mov_b32_e32 v126, v123
	v_mov_b32_e32 v122, v128
	v_mov_b32_e32 v123, v132
	v_mov_b32_e32 v132, v129
	v_mov_b32_e32 v128, v130
	v_mov_b32_e32 v129, v134
	v_mov_b32_e32 v134, v131
	v_pk_add_f32 v[2:3], v[2:3], v[124:125]
	v_pk_add_f32 v[120:121], v[120:121], v[126:127]
	v_pk_add_f32 v[122:123], v[122:123], v[132:133]
	v_pk_add_f32 v[124:125], v[128:129], v[134:135]
	v_pk_add_f32 v[2:3], v[2:3], v[120:121]
	v_pk_add_f32 v[120:121], v[122:123], v[124:125]
	s_nop 0
	v_pk_add_f32 v[2:3], v[2:3], v[120:121]
	s_nop 0
	v_add_f32_e32 v2, v2, v3
	v_fmamk_f32 v2, v2, 0x3a800000, v206
	v_mul_f32_e32 v3, 0x4b800000, v2
	v_cmp_gt_f32_e32 vcc, s101, v2
	s_nop 1
	v_cndmask_b32_e32 v2, v2, v3, vcc
	v_rsq_f32_e32 v2, v2
	s_nop 0
	v_mul_f32_e32 v3, 0x45800000, v2
	v_cndmask_b32_e32 v2, v2, v3, vcc
	ds_write_b32 v203, v2 offset:7168
